# scan-wave inner loop hand-rewritten: merged sa/sy DPP reduction, counted lgkmcnt, 2-step LDS prefetch
# speedup vs baseline: 1.0326x; 1.0326x over previous
.LBB0_850:
	s_barrier
	s_and_saveexec_b64 s[12:13], s[2:3]
	s_xor_b64 s[12:13], exec, s[12:13]
	s_cbranch_execz .LBB0_885
	v_mov_b32_e32 v2, 0
	v_mov_b32_e32 v3, 0
	v_mov_b32_e32 v4, 0
	v_mov_b32_e32 v5, 0
	s_mov_b32 s33, 0
	v_mul_u32_u24_e32 v0, 0x50, v81
	v_and_b32_e32 v98, 63, v200
	s_mov_b32 s30, 0x18000
	v_lshl_add_u32 v98, v98, 2, s30
	v_add_u32_e32 v97, 4, v101
	v_cmp_eq_u32_e64 s[30:31], 8, v81
	v_cndmask_b32_e64 v98, v98, v97, s[4:5]
	s_nop 1
	v_cndmask_b32_e64 v98, v98, v101, s[30:31]
	s_barrier
.Lscan_chunk:
	s_and_b32 s30, s33, 1
	s_mul_i32 s31, s30, 0xa000
	v_add_u32_e32 v94, s31, v0
	s_lshl_b32 s31, s30, 11
	v_add_u32_e32 v95, s31, v100
	v_add_u32_e32 v96, 0x400, v95
	s_lshl_b32 s31, s30, 12
	v_add_u32_e32 v97, s31, v98
	ds_read_b128 v[6:9], v94 offset:0
	ds_read_b128 v[10:13], v94 offset:16
	ds_read_b128 v[14:17], v94 offset:32
	ds_read_b128 v[18:21], v94 offset:48
	ds_read_b128 v[22:25], v94 offset:64
	ds_read2_b32 v[66:67], v95 offset0:0 offset1:16
	ds_read_b128 v[26:29], v94 offset:1280
	ds_read_b128 v[30:33], v94 offset:1296
	ds_read_b128 v[34:37], v94 offset:1312
	ds_read_b128 v[38:41], v94 offset:1328
	ds_read_b128 v[42:45], v94 offset:1344
	s_waitcnt lgkmcnt(5)
	v_pk_mul_f32 v[70:71], v[2:3], v[6:7] op_sel_hi:[0,1]
	v_pk_mul_f32 v[72:73], v[2:3], v[8:9] op_sel:[1,0]
	v_pk_fma_f32 v[70:71], v[4:5], v[10:11], v[70:71] op_sel_hi:[0,1,1]
	v_pk_fma_f32 v[72:73], v[4:5], v[12:13], v[72:73] op_sel:[1,0,0]
	v_pk_add_f32 v[70:71], v[70:71], v[72:73]
	v_pk_mul_f32 v[76:77], v[22:23], v[66:67] op_sel_hi:[1,0]
	v_pk_mul_f32 v[92:93], v[24:25], v[66:67] op_sel_hi:[1,0]
	v_add_f32_dpp v74, v71, v70 row_mirror row_mask:0xf bank_mask:0xf bound_ctrl:1
	v_pk_fma_f32 v[76:77], v[2:3], v[14:15], v[76:77]
	v_pk_fma_f32 v[92:93], v[4:5], v[16:17], v[92:93]
	v_add_f32_dpp v74, v74, v74 row_half_mirror row_mask:0xf bank_mask:0xf bound_ctrl:1
	ds_read_b128 v[46:49], v94 offset:2560
	ds_read_b128 v[50:53], v94 offset:2576
	v_add_f32_dpp v74, v74, v74 quad_perm:[1,0,3,2] row_mask:0xf bank_mask:0xf bound_ctrl:1
	ds_read_b128 v[54:57], v94 offset:2592
	ds_read_b128 v[58:61], v94 offset:2608
	v_add_f32_dpp v74, v74, v74 quad_perm:[2,3,0,1] row_mask:0xf bank_mask:0xf bound_ctrl:1
	ds_read_b128 v[62:65], v94 offset:2624
	ds_write_b32 v97, v74 offset:0
	ds_read2_b32 v[68:69], v95 offset0:32 offset1:48
	v_mov_b32_dpp v74, v74 row_mirror row_mask:0xf bank_mask:0xc
	v_pk_fma_f32 v[2:3], v[18:19], v[74:75], v[76:77] op_sel_hi:[1,0,1]
	v_pk_fma_f32 v[4:5], v[20:21], v[74:75], v[92:93] op_sel_hi:[1,0,1]
	s_waitcnt lgkmcnt(7)
	v_pk_mul_f32 v[70:71], v[2:3], v[26:27] op_sel_hi:[0,1]
	v_pk_mul_f32 v[72:73], v[2:3], v[28:29] op_sel:[1,0]
	v_pk_fma_f32 v[70:71], v[4:5], v[30:31], v[70:71] op_sel_hi:[0,1,1]
	v_pk_fma_f32 v[72:73], v[4:5], v[32:33], v[72:73] op_sel:[1,0,0]
	v_pk_add_f32 v[70:71], v[70:71], v[72:73]
	v_pk_mul_f32 v[76:77], v[42:43], v[66:67] op_sel:[0,1]
	v_pk_mul_f32 v[92:93], v[44:45], v[66:67] op_sel:[0,1]
	v_add_f32_dpp v74, v71, v70 row_mirror row_mask:0xf bank_mask:0xf bound_ctrl:1
	v_pk_fma_f32 v[76:77], v[2:3], v[34:35], v[76:77]
	v_pk_fma_f32 v[92:93], v[4:5], v[36:37], v[92:93]
	v_add_f32_dpp v74, v74, v74 row_half_mirror row_mask:0xf bank_mask:0xf bound_ctrl:1
	ds_read_b128 v[6:9], v94 offset:3840
	ds_read_b128 v[10:13], v94 offset:3856
	v_add_f32_dpp v74, v74, v74 quad_perm:[1,0,3,2] row_mask:0xf bank_mask:0xf bound_ctrl:1
	ds_read_b128 v[14:17], v94 offset:3872
	ds_read_b128 v[18:21], v94 offset:3888
	v_add_f32_dpp v74, v74, v74 quad_perm:[2,3,0,1] row_mask:0xf bank_mask:0xf bound_ctrl:1
	ds_read_b128 v[22:25], v94 offset:3904
	ds_write_b32 v97, v74 offset:8
	v_mov_b32_dpp v74, v74 row_mirror row_mask:0xf bank_mask:0xc
	v_pk_fma_f32 v[2:3], v[38:39], v[74:75], v[76:77] op_sel_hi:[1,0,1]
	v_pk_fma_f32 v[4:5], v[40:41], v[74:75], v[92:93] op_sel_hi:[1,0,1]
	s_waitcnt lgkmcnt(6)
	v_pk_mul_f32 v[70:71], v[2:3], v[46:47] op_sel_hi:[0,1]
	v_pk_mul_f32 v[72:73], v[2:3], v[48:49] op_sel:[1,0]
	v_pk_fma_f32 v[70:71], v[4:5], v[50:51], v[70:71] op_sel_hi:[0,1,1]
	v_pk_fma_f32 v[72:73], v[4:5], v[52:53], v[72:73] op_sel:[1,0,0]
	v_pk_add_f32 v[70:71], v[70:71], v[72:73]
	v_pk_mul_f32 v[76:77], v[62:63], v[68:69] op_sel_hi:[1,0]
	v_pk_mul_f32 v[92:93], v[64:65], v[68:69] op_sel_hi:[1,0]
	v_add_f32_dpp v74, v71, v70 row_mirror row_mask:0xf bank_mask:0xf bound_ctrl:1
	v_pk_fma_f32 v[76:77], v[2:3], v[54:55], v[76:77]
	v_pk_fma_f32 v[92:93], v[4:5], v[56:57], v[92:93]
	v_add_f32_dpp v74, v74, v74 row_half_mirror row_mask:0xf bank_mask:0xf bound_ctrl:1
	ds_read_b128 v[26:29], v94 offset:5120
	ds_read_b128 v[30:33], v94 offset:5136
	v_add_f32_dpp v74, v74, v74 quad_perm:[1,0,3,2] row_mask:0xf bank_mask:0xf bound_ctrl:1
	ds_read_b128 v[34:37], v94 offset:5152
	ds_read_b128 v[38:41], v94 offset:5168
	v_add_f32_dpp v74, v74, v74 quad_perm:[2,3,0,1] row_mask:0xf bank_mask:0xf bound_ctrl:1
	ds_read_b128 v[42:45], v94 offset:5184
	ds_write_b32 v97, v74 offset:256
	ds_read2_b32 v[66:67], v95 offset0:64 offset1:80
	v_mov_b32_dpp v74, v74 row_mirror row_mask:0xf bank_mask:0xc
	v_pk_fma_f32 v[2:3], v[58:59], v[74:75], v[76:77] op_sel_hi:[1,0,1]
	v_pk_fma_f32 v[4:5], v[60:61], v[74:75], v[92:93] op_sel_hi:[1,0,1]
	s_waitcnt lgkmcnt(8)
	v_pk_mul_f32 v[70:71], v[2:3], v[6:7] op_sel_hi:[0,1]
	v_pk_mul_f32 v[72:73], v[2:3], v[8:9] op_sel:[1,0]
	v_pk_fma_f32 v[70:71], v[4:5], v[10:11], v[70:71] op_sel_hi:[0,1,1]
	v_pk_fma_f32 v[72:73], v[4:5], v[12:13], v[72:73] op_sel:[1,0,0]
	v_pk_add_f32 v[70:71], v[70:71], v[72:73]
	v_pk_mul_f32 v[76:77], v[22:23], v[68:69] op_sel:[0,1]
	v_pk_mul_f32 v[92:93], v[24:25], v[68:69] op_sel:[0,1]
	v_add_f32_dpp v74, v71, v70 row_mirror row_mask:0xf bank_mask:0xf bound_ctrl:1
	v_pk_fma_f32 v[76:77], v[2:3], v[14:15], v[76:77]
	v_pk_fma_f32 v[92:93], v[4:5], v[16:17], v[92:93]
	v_add_f32_dpp v74, v74, v74 row_half_mirror row_mask:0xf bank_mask:0xf bound_ctrl:1
	ds_read_b128 v[46:49], v94 offset:6400
	ds_read_b128 v[50:53], v94 offset:6416
	v_add_f32_dpp v74, v74, v74 quad_perm:[1,0,3,2] row_mask:0xf bank_mask:0xf bound_ctrl:1
	ds_read_b128 v[54:57], v94 offset:6432
	ds_read_b128 v[58:61], v94 offset:6448
	v_add_f32_dpp v74, v74, v74 quad_perm:[2,3,0,1] row_mask:0xf bank_mask:0xf bound_ctrl:1
	ds_read_b128 v[62:65], v94 offset:6464
	ds_write_b32 v97, v74 offset:264
	v_mov_b32_dpp v74, v74 row_mirror row_mask:0xf bank_mask:0xc
	v_pk_fma_f32 v[2:3], v[18:19], v[74:75], v[76:77] op_sel_hi:[1,0,1]
	v_pk_fma_f32 v[4:5], v[20:21], v[74:75], v[92:93] op_sel_hi:[1,0,1]
	s_waitcnt lgkmcnt(6)
	v_pk_mul_f32 v[70:71], v[2:3], v[26:27] op_sel_hi:[0,1]
	v_pk_mul_f32 v[72:73], v[2:3], v[28:29] op_sel:[1,0]
	v_pk_fma_f32 v[70:71], v[4:5], v[30:31], v[70:71] op_sel_hi:[0,1,1]
	v_pk_fma_f32 v[72:73], v[4:5], v[32:33], v[72:73] op_sel:[1,0,0]
	v_pk_add_f32 v[70:71], v[70:71], v[72:73]
	v_pk_mul_f32 v[76:77], v[42:43], v[66:67] op_sel_hi:[1,0]
	v_pk_mul_f32 v[92:93], v[44:45], v[66:67] op_sel_hi:[1,0]
	v_add_f32_dpp v74, v71, v70 row_mirror row_mask:0xf bank_mask:0xf bound_ctrl:1
	v_pk_fma_f32 v[76:77], v[2:3], v[34:35], v[76:77]
	v_pk_fma_f32 v[92:93], v[4:5], v[36:37], v[92:93]
	v_add_f32_dpp v74, v74, v74 row_half_mirror row_mask:0xf bank_mask:0xf bound_ctrl:1
	ds_read_b128 v[6:9], v94 offset:7680
	ds_read_b128 v[10:13], v94 offset:7696
	v_add_f32_dpp v74, v74, v74 quad_perm:[1,0,3,2] row_mask:0xf bank_mask:0xf bound_ctrl:1
	ds_read_b128 v[14:17], v94 offset:7712
	ds_read_b128 v[18:21], v94 offset:7728
	v_add_f32_dpp v74, v74, v74 quad_perm:[2,3,0,1] row_mask:0xf bank_mask:0xf bound_ctrl:1
	ds_read_b128 v[22:25], v94 offset:7744
	ds_write_b32 v97, v74 offset:512
	ds_read2_b32 v[68:69], v95 offset0:96 offset1:112
	v_mov_b32_dpp v74, v74 row_mirror row_mask:0xf bank_mask:0xc
	v_pk_fma_f32 v[2:3], v[38:39], v[74:75], v[76:77] op_sel_hi:[1,0,1]
	v_pk_fma_f32 v[4:5], v[40:41], v[74:75], v[92:93] op_sel_hi:[1,0,1]
	s_waitcnt lgkmcnt(8)
	v_pk_mul_f32 v[70:71], v[2:3], v[46:47] op_sel_hi:[0,1]
	v_pk_mul_f32 v[72:73], v[2:3], v[48:49] op_sel:[1,0]
	v_pk_fma_f32 v[70:71], v[4:5], v[50:51], v[70:71] op_sel_hi:[0,1,1]
	v_pk_fma_f32 v[72:73], v[4:5], v[52:53], v[72:73] op_sel:[1,0,0]
	v_pk_add_f32 v[70:71], v[70:71], v[72:73]
	v_pk_mul_f32 v[76:77], v[62:63], v[66:67] op_sel:[0,1]
	v_pk_mul_f32 v[92:93], v[64:65], v[66:67] op_sel:[0,1]
	v_add_f32_dpp v74, v71, v70 row_mirror row_mask:0xf bank_mask:0xf bound_ctrl:1
	v_pk_fma_f32 v[76:77], v[2:3], v[54:55], v[76:77]
	v_pk_fma_f32 v[92:93], v[4:5], v[56:57], v[92:93]
	v_add_f32_dpp v74, v74, v74 row_half_mirror row_mask:0xf bank_mask:0xf bound_ctrl:1
	ds_read_b128 v[26:29], v94 offset:8960
	ds_read_b128 v[30:33], v94 offset:8976
	v_add_f32_dpp v74, v74, v74 quad_perm:[1,0,3,2] row_mask:0xf bank_mask:0xf bound_ctrl:1
	ds_read_b128 v[34:37], v94 offset:8992
	ds_read_b128 v[38:41], v94 offset:9008
	v_add_f32_dpp v74, v74, v74 quad_perm:[2,3,0,1] row_mask:0xf bank_mask:0xf bound_ctrl:1
	ds_read_b128 v[42:45], v94 offset:9024
	ds_write_b32 v97, v74 offset:520
	v_mov_b32_dpp v74, v74 row_mirror row_mask:0xf bank_mask:0xc
	v_pk_fma_f32 v[2:3], v[58:59], v[74:75], v[76:77] op_sel_hi:[1,0,1]
	v_pk_fma_f32 v[4:5], v[60:61], v[74:75], v[92:93] op_sel_hi:[1,0,1]
	s_waitcnt lgkmcnt(6)
	v_pk_mul_f32 v[70:71], v[2:3], v[6:7] op_sel_hi:[0,1]
	v_pk_mul_f32 v[72:73], v[2:3], v[8:9] op_sel:[1,0]
	v_pk_fma_f32 v[70:71], v[4:5], v[10:11], v[70:71] op_sel_hi:[0,1,1]
	v_pk_fma_f32 v[72:73], v[4:5], v[12:13], v[72:73] op_sel:[1,0,0]
	v_pk_add_f32 v[70:71], v[70:71], v[72:73]
	v_pk_mul_f32 v[76:77], v[22:23], v[68:69] op_sel_hi:[1,0]
	v_pk_mul_f32 v[92:93], v[24:25], v[68:69] op_sel_hi:[1,0]
	v_add_f32_dpp v74, v71, v70 row_mirror row_mask:0xf bank_mask:0xf bound_ctrl:1
	v_pk_fma_f32 v[76:77], v[2:3], v[14:15], v[76:77]
	v_pk_fma_f32 v[92:93], v[4:5], v[16:17], v[92:93]
	v_add_f32_dpp v74, v74, v74 row_half_mirror row_mask:0xf bank_mask:0xf bound_ctrl:1
	ds_read_b128 v[46:49], v94 offset:10240
	ds_read_b128 v[50:53], v94 offset:10256
	v_add_f32_dpp v74, v74, v74 quad_perm:[1,0,3,2] row_mask:0xf bank_mask:0xf bound_ctrl:1
	ds_read_b128 v[54:57], v94 offset:10272
	ds_read_b128 v[58:61], v94 offset:10288
	v_add_f32_dpp v74, v74, v74 quad_perm:[2,3,0,1] row_mask:0xf bank_mask:0xf bound_ctrl:1
	ds_read_b128 v[62:65], v94 offset:10304
	ds_write_b32 v97, v74 offset:768
	ds_read2_b32 v[66:67], v95 offset0:128 offset1:144
	v_mov_b32_dpp v74, v74 row_mirror row_mask:0xf bank_mask:0xc
	v_pk_fma_f32 v[2:3], v[18:19], v[74:75], v[76:77] op_sel_hi:[1,0,1]
	v_pk_fma_f32 v[4:5], v[20:21], v[74:75], v[92:93] op_sel_hi:[1,0,1]
	s_waitcnt lgkmcnt(8)
	v_pk_mul_f32 v[70:71], v[2:3], v[26:27] op_sel_hi:[0,1]
	v_pk_mul_f32 v[72:73], v[2:3], v[28:29] op_sel:[1,0]
	v_pk_fma_f32 v[70:71], v[4:5], v[30:31], v[70:71] op_sel_hi:[0,1,1]
	v_pk_fma_f32 v[72:73], v[4:5], v[32:33], v[72:73] op_sel:[1,0,0]
	v_pk_add_f32 v[70:71], v[70:71], v[72:73]
	v_pk_mul_f32 v[76:77], v[42:43], v[68:69] op_sel:[0,1]
	v_pk_mul_f32 v[92:93], v[44:45], v[68:69] op_sel:[0,1]
	v_add_f32_dpp v74, v71, v70 row_mirror row_mask:0xf bank_mask:0xf bound_ctrl:1
	v_pk_fma_f32 v[76:77], v[2:3], v[34:35], v[76:77]
	v_pk_fma_f32 v[92:93], v[4:5], v[36:37], v[92:93]
	v_add_f32_dpp v74, v74, v74 row_half_mirror row_mask:0xf bank_mask:0xf bound_ctrl:1
	ds_read_b128 v[6:9], v94 offset:11520
	ds_read_b128 v[10:13], v94 offset:11536
	v_add_f32_dpp v74, v74, v74 quad_perm:[1,0,3,2] row_mask:0xf bank_mask:0xf bound_ctrl:1
	ds_read_b128 v[14:17], v94 offset:11552
	ds_read_b128 v[18:21], v94 offset:11568
	v_add_f32_dpp v74, v74, v74 quad_perm:[2,3,0,1] row_mask:0xf bank_mask:0xf bound_ctrl:1
	ds_read_b128 v[22:25], v94 offset:11584
	ds_write_b32 v97, v74 offset:776
	v_mov_b32_dpp v74, v74 row_mirror row_mask:0xf bank_mask:0xc
	v_pk_fma_f32 v[2:3], v[38:39], v[74:75], v[76:77] op_sel_hi:[1,0,1]
	v_pk_fma_f32 v[4:5], v[40:41], v[74:75], v[92:93] op_sel_hi:[1,0,1]
	s_waitcnt lgkmcnt(6)
	v_pk_mul_f32 v[70:71], v[2:3], v[46:47] op_sel_hi:[0,1]
	v_pk_mul_f32 v[72:73], v[2:3], v[48:49] op_sel:[1,0]
	v_pk_fma_f32 v[70:71], v[4:5], v[50:51], v[70:71] op_sel_hi:[0,1,1]
	v_pk_fma_f32 v[72:73], v[4:5], v[52:53], v[72:73] op_sel:[1,0,0]
	v_pk_add_f32 v[70:71], v[70:71], v[72:73]
	v_pk_mul_f32 v[76:77], v[62:63], v[66:67] op_sel_hi:[1,0]
	v_pk_mul_f32 v[92:93], v[64:65], v[66:67] op_sel_hi:[1,0]
	v_add_f32_dpp v74, v71, v70 row_mirror row_mask:0xf bank_mask:0xf bound_ctrl:1
	v_pk_fma_f32 v[76:77], v[2:3], v[54:55], v[76:77]
	v_pk_fma_f32 v[92:93], v[4:5], v[56:57], v[92:93]
	v_add_f32_dpp v74, v74, v74 row_half_mirror row_mask:0xf bank_mask:0xf bound_ctrl:1
	ds_read_b128 v[26:29], v94 offset:12800
	ds_read_b128 v[30:33], v94 offset:12816
	v_add_f32_dpp v74, v74, v74 quad_perm:[1,0,3,2] row_mask:0xf bank_mask:0xf bound_ctrl:1
	ds_read_b128 v[34:37], v94 offset:12832
	ds_read_b128 v[38:41], v94 offset:12848
	v_add_f32_dpp v74, v74, v74 quad_perm:[2,3,0,1] row_mask:0xf bank_mask:0xf bound_ctrl:1
	ds_read_b128 v[42:45], v94 offset:12864
	ds_write_b32 v97, v74 offset:1024
	ds_read2_b32 v[68:69], v95 offset0:160 offset1:176
	v_mov_b32_dpp v74, v74 row_mirror row_mask:0xf bank_mask:0xc
	v_pk_fma_f32 v[2:3], v[58:59], v[74:75], v[76:77] op_sel_hi:[1,0,1]
	v_pk_fma_f32 v[4:5], v[60:61], v[74:75], v[92:93] op_sel_hi:[1,0,1]
	s_waitcnt lgkmcnt(8)
	v_pk_mul_f32 v[70:71], v[2:3], v[6:7] op_sel_hi:[0,1]
	v_pk_mul_f32 v[72:73], v[2:3], v[8:9] op_sel:[1,0]
	v_pk_fma_f32 v[70:71], v[4:5], v[10:11], v[70:71] op_sel_hi:[0,1,1]
	v_pk_fma_f32 v[72:73], v[4:5], v[12:13], v[72:73] op_sel:[1,0,0]
	v_pk_add_f32 v[70:71], v[70:71], v[72:73]
	v_pk_mul_f32 v[76:77], v[22:23], v[66:67] op_sel:[0,1]
	v_pk_mul_f32 v[92:93], v[24:25], v[66:67] op_sel:[0,1]
	v_add_f32_dpp v74, v71, v70 row_mirror row_mask:0xf bank_mask:0xf bound_ctrl:1
	v_pk_fma_f32 v[76:77], v[2:3], v[14:15], v[76:77]
	v_pk_fma_f32 v[92:93], v[4:5], v[16:17], v[92:93]
	v_add_f32_dpp v74, v74, v74 row_half_mirror row_mask:0xf bank_mask:0xf bound_ctrl:1
	ds_read_b128 v[46:49], v94 offset:14080
	ds_read_b128 v[50:53], v94 offset:14096
	v_add_f32_dpp v74, v74, v74 quad_perm:[1,0,3,2] row_mask:0xf bank_mask:0xf bound_ctrl:1
	ds_read_b128 v[54:57], v94 offset:14112
	ds_read_b128 v[58:61], v94 offset:14128
	v_add_f32_dpp v74, v74, v74 quad_perm:[2,3,0,1] row_mask:0xf bank_mask:0xf bound_ctrl:1
	ds_read_b128 v[62:65], v94 offset:14144
	ds_write_b32 v97, v74 offset:1032
	v_mov_b32_dpp v74, v74 row_mirror row_mask:0xf bank_mask:0xc
	v_pk_fma_f32 v[2:3], v[18:19], v[74:75], v[76:77] op_sel_hi:[1,0,1]
	v_pk_fma_f32 v[4:5], v[20:21], v[74:75], v[92:93] op_sel_hi:[1,0,1]
	s_waitcnt lgkmcnt(6)
	v_pk_mul_f32 v[70:71], v[2:3], v[26:27] op_sel_hi:[0,1]
	v_pk_mul_f32 v[72:73], v[2:3], v[28:29] op_sel:[1,0]
	v_pk_fma_f32 v[70:71], v[4:5], v[30:31], v[70:71] op_sel_hi:[0,1,1]
	v_pk_fma_f32 v[72:73], v[4:5], v[32:33], v[72:73] op_sel:[1,0,0]
	v_pk_add_f32 v[70:71], v[70:71], v[72:73]
	v_pk_mul_f32 v[76:77], v[42:43], v[68:69] op_sel_hi:[1,0]
	v_pk_mul_f32 v[92:93], v[44:45], v[68:69] op_sel_hi:[1,0]
	v_add_f32_dpp v74, v71, v70 row_mirror row_mask:0xf bank_mask:0xf bound_ctrl:1
	v_pk_fma_f32 v[76:77], v[2:3], v[34:35], v[76:77]
	v_pk_fma_f32 v[92:93], v[4:5], v[36:37], v[92:93]
	v_add_f32_dpp v74, v74, v74 row_half_mirror row_mask:0xf bank_mask:0xf bound_ctrl:1
	ds_read_b128 v[6:9], v94 offset:15360
	ds_read_b128 v[10:13], v94 offset:15376
	v_add_f32_dpp v74, v74, v74 quad_perm:[1,0,3,2] row_mask:0xf bank_mask:0xf bound_ctrl:1
	ds_read_b128 v[14:17], v94 offset:15392
	ds_read_b128 v[18:21], v94 offset:15408
	v_add_f32_dpp v74, v74, v74 quad_perm:[2,3,0,1] row_mask:0xf bank_mask:0xf bound_ctrl:1
	ds_read_b128 v[22:25], v94 offset:15424
	ds_write_b32 v97, v74 offset:1280
	ds_read2_b32 v[66:67], v95 offset0:192 offset1:208
	v_mov_b32_dpp v74, v74 row_mirror row_mask:0xf bank_mask:0xc
	v_pk_fma_f32 v[2:3], v[38:39], v[74:75], v[76:77] op_sel_hi:[1,0,1]
	v_pk_fma_f32 v[4:5], v[40:41], v[74:75], v[92:93] op_sel_hi:[1,0,1]
	s_waitcnt lgkmcnt(8)
	v_pk_mul_f32 v[70:71], v[2:3], v[46:47] op_sel_hi:[0,1]
	v_pk_mul_f32 v[72:73], v[2:3], v[48:49] op_sel:[1,0]
	v_pk_fma_f32 v[70:71], v[4:5], v[50:51], v[70:71] op_sel_hi:[0,1,1]
	v_pk_fma_f32 v[72:73], v[4:5], v[52:53], v[72:73] op_sel:[1,0,0]
	v_pk_add_f32 v[70:71], v[70:71], v[72:73]
	v_pk_mul_f32 v[76:77], v[62:63], v[68:69] op_sel:[0,1]
	v_pk_mul_f32 v[92:93], v[64:65], v[68:69] op_sel:[0,1]
	v_add_f32_dpp v74, v71, v70 row_mirror row_mask:0xf bank_mask:0xf bound_ctrl:1
	v_pk_fma_f32 v[76:77], v[2:3], v[54:55], v[76:77]
	v_pk_fma_f32 v[92:93], v[4:5], v[56:57], v[92:93]
	v_add_f32_dpp v74, v74, v74 row_half_mirror row_mask:0xf bank_mask:0xf bound_ctrl:1
	ds_read_b128 v[26:29], v94 offset:16640
	ds_read_b128 v[30:33], v94 offset:16656
	v_add_f32_dpp v74, v74, v74 quad_perm:[1,0,3,2] row_mask:0xf bank_mask:0xf bound_ctrl:1
	ds_read_b128 v[34:37], v94 offset:16672
	ds_read_b128 v[38:41], v94 offset:16688
	v_add_f32_dpp v74, v74, v74 quad_perm:[2,3,0,1] row_mask:0xf bank_mask:0xf bound_ctrl:1
	ds_read_b128 v[42:45], v94 offset:16704
	ds_write_b32 v97, v74 offset:1288
	v_mov_b32_dpp v74, v74 row_mirror row_mask:0xf bank_mask:0xc
	v_pk_fma_f32 v[2:3], v[58:59], v[74:75], v[76:77] op_sel_hi:[1,0,1]
	v_pk_fma_f32 v[4:5], v[60:61], v[74:75], v[92:93] op_sel_hi:[1,0,1]
	s_waitcnt lgkmcnt(6)
	v_pk_mul_f32 v[70:71], v[2:3], v[6:7] op_sel_hi:[0,1]
	v_pk_mul_f32 v[72:73], v[2:3], v[8:9] op_sel:[1,0]
	v_pk_fma_f32 v[70:71], v[4:5], v[10:11], v[70:71] op_sel_hi:[0,1,1]
	v_pk_fma_f32 v[72:73], v[4:5], v[12:13], v[72:73] op_sel:[1,0,0]
	v_pk_add_f32 v[70:71], v[70:71], v[72:73]
	v_pk_mul_f32 v[76:77], v[22:23], v[66:67] op_sel_hi:[1,0]
	v_pk_mul_f32 v[92:93], v[24:25], v[66:67] op_sel_hi:[1,0]
	v_add_f32_dpp v74, v71, v70 row_mirror row_mask:0xf bank_mask:0xf bound_ctrl:1
	v_pk_fma_f32 v[76:77], v[2:3], v[14:15], v[76:77]
	v_pk_fma_f32 v[92:93], v[4:5], v[16:17], v[92:93]
	v_add_f32_dpp v74, v74, v74 row_half_mirror row_mask:0xf bank_mask:0xf bound_ctrl:1
	ds_read_b128 v[46:49], v94 offset:17920
	ds_read_b128 v[50:53], v94 offset:17936
	v_add_f32_dpp v74, v74, v74 quad_perm:[1,0,3,2] row_mask:0xf bank_mask:0xf bound_ctrl:1
	ds_read_b128 v[54:57], v94 offset:17952
	ds_read_b128 v[58:61], v94 offset:17968
	v_add_f32_dpp v74, v74, v74 quad_perm:[2,3,0,1] row_mask:0xf bank_mask:0xf bound_ctrl:1
	ds_read_b128 v[62:65], v94 offset:17984
	ds_write_b32 v97, v74 offset:1536
	ds_read2_b32 v[68:69], v95 offset0:224 offset1:240
	v_mov_b32_dpp v74, v74 row_mirror row_mask:0xf bank_mask:0xc
	v_pk_fma_f32 v[2:3], v[18:19], v[74:75], v[76:77] op_sel_hi:[1,0,1]
	v_pk_fma_f32 v[4:5], v[20:21], v[74:75], v[92:93] op_sel_hi:[1,0,1]
	s_waitcnt lgkmcnt(8)
	v_pk_mul_f32 v[70:71], v[2:3], v[26:27] op_sel_hi:[0,1]
	v_pk_mul_f32 v[72:73], v[2:3], v[28:29] op_sel:[1,0]
	v_pk_fma_f32 v[70:71], v[4:5], v[30:31], v[70:71] op_sel_hi:[0,1,1]
	v_pk_fma_f32 v[72:73], v[4:5], v[32:33], v[72:73] op_sel:[1,0,0]
	v_pk_add_f32 v[70:71], v[70:71], v[72:73]
	v_pk_mul_f32 v[76:77], v[42:43], v[66:67] op_sel:[0,1]
	v_pk_mul_f32 v[92:93], v[44:45], v[66:67] op_sel:[0,1]
	v_add_f32_dpp v74, v71, v70 row_mirror row_mask:0xf bank_mask:0xf bound_ctrl:1
	v_pk_fma_f32 v[76:77], v[2:3], v[34:35], v[76:77]
	v_pk_fma_f32 v[92:93], v[4:5], v[36:37], v[92:93]
	v_add_f32_dpp v74, v74, v74 row_half_mirror row_mask:0xf bank_mask:0xf bound_ctrl:1
	ds_read_b128 v[6:9], v94 offset:19200
	ds_read_b128 v[10:13], v94 offset:19216
	v_add_f32_dpp v74, v74, v74 quad_perm:[1,0,3,2] row_mask:0xf bank_mask:0xf bound_ctrl:1
	ds_read_b128 v[14:17], v94 offset:19232
	ds_read_b128 v[18:21], v94 offset:19248
	v_add_f32_dpp v74, v74, v74 quad_perm:[2,3,0,1] row_mask:0xf bank_mask:0xf bound_ctrl:1
	ds_read_b128 v[22:25], v94 offset:19264
	ds_write_b32 v97, v74 offset:1544
	v_mov_b32_dpp v74, v74 row_mirror row_mask:0xf bank_mask:0xc
	v_pk_fma_f32 v[2:3], v[38:39], v[74:75], v[76:77] op_sel_hi:[1,0,1]
	v_pk_fma_f32 v[4:5], v[40:41], v[74:75], v[92:93] op_sel_hi:[1,0,1]
	s_waitcnt lgkmcnt(6)
	v_pk_mul_f32 v[70:71], v[2:3], v[46:47] op_sel_hi:[0,1]
	v_pk_mul_f32 v[72:73], v[2:3], v[48:49] op_sel:[1,0]
	v_pk_fma_f32 v[70:71], v[4:5], v[50:51], v[70:71] op_sel_hi:[0,1,1]
	v_pk_fma_f32 v[72:73], v[4:5], v[52:53], v[72:73] op_sel:[1,0,0]
	v_pk_add_f32 v[70:71], v[70:71], v[72:73]
	v_pk_mul_f32 v[76:77], v[62:63], v[68:69] op_sel_hi:[1,0]
	v_pk_mul_f32 v[92:93], v[64:65], v[68:69] op_sel_hi:[1,0]
	v_add_f32_dpp v74, v71, v70 row_mirror row_mask:0xf bank_mask:0xf bound_ctrl:1
	v_pk_fma_f32 v[76:77], v[2:3], v[54:55], v[76:77]
	v_pk_fma_f32 v[92:93], v[4:5], v[56:57], v[92:93]
	v_add_f32_dpp v74, v74, v74 row_half_mirror row_mask:0xf bank_mask:0xf bound_ctrl:1
	ds_read_b128 v[26:29], v94 offset:20480
	ds_read_b128 v[30:33], v94 offset:20496
	v_add_f32_dpp v74, v74, v74 quad_perm:[1,0,3,2] row_mask:0xf bank_mask:0xf bound_ctrl:1
	ds_read_b128 v[34:37], v94 offset:20512
	ds_read_b128 v[38:41], v94 offset:20528
	v_add_f32_dpp v74, v74, v74 quad_perm:[2,3,0,1] row_mask:0xf bank_mask:0xf bound_ctrl:1
	ds_read_b128 v[42:45], v94 offset:20544
	ds_write_b32 v97, v74 offset:1792
	ds_read2_b32 v[66:67], v96 offset0:0 offset1:16
	v_mov_b32_dpp v74, v74 row_mirror row_mask:0xf bank_mask:0xc
	v_pk_fma_f32 v[2:3], v[58:59], v[74:75], v[76:77] op_sel_hi:[1,0,1]
	v_pk_fma_f32 v[4:5], v[60:61], v[74:75], v[92:93] op_sel_hi:[1,0,1]
	s_waitcnt lgkmcnt(8)
	v_pk_mul_f32 v[70:71], v[2:3], v[6:7] op_sel_hi:[0,1]
	v_pk_mul_f32 v[72:73], v[2:3], v[8:9] op_sel:[1,0]
	v_pk_fma_f32 v[70:71], v[4:5], v[10:11], v[70:71] op_sel_hi:[0,1,1]
	v_pk_fma_f32 v[72:73], v[4:5], v[12:13], v[72:73] op_sel:[1,0,0]
	v_pk_add_f32 v[70:71], v[70:71], v[72:73]
	v_pk_mul_f32 v[76:77], v[22:23], v[68:69] op_sel:[0,1]
	v_pk_mul_f32 v[92:93], v[24:25], v[68:69] op_sel:[0,1]
	v_add_f32_dpp v74, v71, v70 row_mirror row_mask:0xf bank_mask:0xf bound_ctrl:1
	v_pk_fma_f32 v[76:77], v[2:3], v[14:15], v[76:77]
	v_pk_fma_f32 v[92:93], v[4:5], v[16:17], v[92:93]
	v_add_f32_dpp v74, v74, v74 row_half_mirror row_mask:0xf bank_mask:0xf bound_ctrl:1
	ds_read_b128 v[46:49], v94 offset:21760
	ds_read_b128 v[50:53], v94 offset:21776
	v_add_f32_dpp v74, v74, v74 quad_perm:[1,0,3,2] row_mask:0xf bank_mask:0xf bound_ctrl:1
	ds_read_b128 v[54:57], v94 offset:21792
	ds_read_b128 v[58:61], v94 offset:21808
	v_add_f32_dpp v74, v74, v74 quad_perm:[2,3,0,1] row_mask:0xf bank_mask:0xf bound_ctrl:1
	ds_read_b128 v[62:65], v94 offset:21824
	ds_write_b32 v97, v74 offset:1800
	v_mov_b32_dpp v74, v74 row_mirror row_mask:0xf bank_mask:0xc
	v_pk_fma_f32 v[2:3], v[18:19], v[74:75], v[76:77] op_sel_hi:[1,0,1]
	v_pk_fma_f32 v[4:5], v[20:21], v[74:75], v[92:93] op_sel_hi:[1,0,1]
	s_waitcnt lgkmcnt(6)
	v_pk_mul_f32 v[70:71], v[2:3], v[26:27] op_sel_hi:[0,1]
	v_pk_mul_f32 v[72:73], v[2:3], v[28:29] op_sel:[1,0]
	v_pk_fma_f32 v[70:71], v[4:5], v[30:31], v[70:71] op_sel_hi:[0,1,1]
	v_pk_fma_f32 v[72:73], v[4:5], v[32:33], v[72:73] op_sel:[1,0,0]
	v_pk_add_f32 v[70:71], v[70:71], v[72:73]
	v_pk_mul_f32 v[76:77], v[42:43], v[66:67] op_sel_hi:[1,0]
	v_pk_mul_f32 v[92:93], v[44:45], v[66:67] op_sel_hi:[1,0]
	v_add_f32_dpp v74, v71, v70 row_mirror row_mask:0xf bank_mask:0xf bound_ctrl:1
	v_pk_fma_f32 v[76:77], v[2:3], v[34:35], v[76:77]
	v_pk_fma_f32 v[92:93], v[4:5], v[36:37], v[92:93]
	v_add_f32_dpp v74, v74, v74 row_half_mirror row_mask:0xf bank_mask:0xf bound_ctrl:1
	ds_read_b128 v[6:9], v94 offset:23040
	ds_read_b128 v[10:13], v94 offset:23056
	v_add_f32_dpp v74, v74, v74 quad_perm:[1,0,3,2] row_mask:0xf bank_mask:0xf bound_ctrl:1
	ds_read_b128 v[14:17], v94 offset:23072
	ds_read_b128 v[18:21], v94 offset:23088
	v_add_f32_dpp v74, v74, v74 quad_perm:[2,3,0,1] row_mask:0xf bank_mask:0xf bound_ctrl:1
	ds_read_b128 v[22:25], v94 offset:23104
	ds_write_b32 v97, v74 offset:2048
	ds_read2_b32 v[68:69], v96 offset0:32 offset1:48
	v_mov_b32_dpp v74, v74 row_mirror row_mask:0xf bank_mask:0xc
	v_pk_fma_f32 v[2:3], v[38:39], v[74:75], v[76:77] op_sel_hi:[1,0,1]
	v_pk_fma_f32 v[4:5], v[40:41], v[74:75], v[92:93] op_sel_hi:[1,0,1]
	s_waitcnt lgkmcnt(8)
	v_pk_mul_f32 v[70:71], v[2:3], v[46:47] op_sel_hi:[0,1]
	v_pk_mul_f32 v[72:73], v[2:3], v[48:49] op_sel:[1,0]
	v_pk_fma_f32 v[70:71], v[4:5], v[50:51], v[70:71] op_sel_hi:[0,1,1]
	v_pk_fma_f32 v[72:73], v[4:5], v[52:53], v[72:73] op_sel:[1,0,0]
	v_pk_add_f32 v[70:71], v[70:71], v[72:73]
	v_pk_mul_f32 v[76:77], v[62:63], v[66:67] op_sel:[0,1]
	v_pk_mul_f32 v[92:93], v[64:65], v[66:67] op_sel:[0,1]
	v_add_f32_dpp v74, v71, v70 row_mirror row_mask:0xf bank_mask:0xf bound_ctrl:1
	v_pk_fma_f32 v[76:77], v[2:3], v[54:55], v[76:77]
	v_pk_fma_f32 v[92:93], v[4:5], v[56:57], v[92:93]
	v_add_f32_dpp v74, v74, v74 row_half_mirror row_mask:0xf bank_mask:0xf bound_ctrl:1
	ds_read_b128 v[26:29], v94 offset:24320
	ds_read_b128 v[30:33], v94 offset:24336
	v_add_f32_dpp v74, v74, v74 quad_perm:[1,0,3,2] row_mask:0xf bank_mask:0xf bound_ctrl:1
	ds_read_b128 v[34:37], v94 offset:24352
	ds_read_b128 v[38:41], v94 offset:24368
	v_add_f32_dpp v74, v74, v74 quad_perm:[2,3,0,1] row_mask:0xf bank_mask:0xf bound_ctrl:1
	ds_read_b128 v[42:45], v94 offset:24384
	ds_write_b32 v97, v74 offset:2056
	v_mov_b32_dpp v74, v74 row_mirror row_mask:0xf bank_mask:0xc
	v_pk_fma_f32 v[2:3], v[58:59], v[74:75], v[76:77] op_sel_hi:[1,0,1]
	v_pk_fma_f32 v[4:5], v[60:61], v[74:75], v[92:93] op_sel_hi:[1,0,1]
	s_waitcnt lgkmcnt(6)
	v_pk_mul_f32 v[70:71], v[2:3], v[6:7] op_sel_hi:[0,1]
	v_pk_mul_f32 v[72:73], v[2:3], v[8:9] op_sel:[1,0]
	v_pk_fma_f32 v[70:71], v[4:5], v[10:11], v[70:71] op_sel_hi:[0,1,1]
	v_pk_fma_f32 v[72:73], v[4:5], v[12:13], v[72:73] op_sel:[1,0,0]
	v_pk_add_f32 v[70:71], v[70:71], v[72:73]
	v_pk_mul_f32 v[76:77], v[22:23], v[68:69] op_sel_hi:[1,0]
	v_pk_mul_f32 v[92:93], v[24:25], v[68:69] op_sel_hi:[1,0]
	v_add_f32_dpp v74, v71, v70 row_mirror row_mask:0xf bank_mask:0xf bound_ctrl:1
	v_pk_fma_f32 v[76:77], v[2:3], v[14:15], v[76:77]
	v_pk_fma_f32 v[92:93], v[4:5], v[16:17], v[92:93]
	v_add_f32_dpp v74, v74, v74 row_half_mirror row_mask:0xf bank_mask:0xf bound_ctrl:1
	ds_read_b128 v[46:49], v94 offset:25600
	ds_read_b128 v[50:53], v94 offset:25616
	v_add_f32_dpp v74, v74, v74 quad_perm:[1,0,3,2] row_mask:0xf bank_mask:0xf bound_ctrl:1
	ds_read_b128 v[54:57], v94 offset:25632
	ds_read_b128 v[58:61], v94 offset:25648
	v_add_f32_dpp v74, v74, v74 quad_perm:[2,3,0,1] row_mask:0xf bank_mask:0xf bound_ctrl:1
	ds_read_b128 v[62:65], v94 offset:25664
	ds_write_b32 v97, v74 offset:2304
	ds_read2_b32 v[66:67], v96 offset0:64 offset1:80
	v_mov_b32_dpp v74, v74 row_mirror row_mask:0xf bank_mask:0xc
	v_pk_fma_f32 v[2:3], v[18:19], v[74:75], v[76:77] op_sel_hi:[1,0,1]
	v_pk_fma_f32 v[4:5], v[20:21], v[74:75], v[92:93] op_sel_hi:[1,0,1]
	s_waitcnt lgkmcnt(8)
	v_pk_mul_f32 v[70:71], v[2:3], v[26:27] op_sel_hi:[0,1]
	v_pk_mul_f32 v[72:73], v[2:3], v[28:29] op_sel:[1,0]
	v_pk_fma_f32 v[70:71], v[4:5], v[30:31], v[70:71] op_sel_hi:[0,1,1]
	v_pk_fma_f32 v[72:73], v[4:5], v[32:33], v[72:73] op_sel:[1,0,0]
	v_pk_add_f32 v[70:71], v[70:71], v[72:73]
	v_pk_mul_f32 v[76:77], v[42:43], v[68:69] op_sel:[0,1]
	v_pk_mul_f32 v[92:93], v[44:45], v[68:69] op_sel:[0,1]
	v_add_f32_dpp v74, v71, v70 row_mirror row_mask:0xf bank_mask:0xf bound_ctrl:1
	v_pk_fma_f32 v[76:77], v[2:3], v[34:35], v[76:77]
	v_pk_fma_f32 v[92:93], v[4:5], v[36:37], v[92:93]
	v_add_f32_dpp v74, v74, v74 row_half_mirror row_mask:0xf bank_mask:0xf bound_ctrl:1
	ds_read_b128 v[6:9], v94 offset:26880
	ds_read_b128 v[10:13], v94 offset:26896
	v_add_f32_dpp v74, v74, v74 quad_perm:[1,0,3,2] row_mask:0xf bank_mask:0xf bound_ctrl:1
	ds_read_b128 v[14:17], v94 offset:26912
	ds_read_b128 v[18:21], v94 offset:26928
	v_add_f32_dpp v74, v74, v74 quad_perm:[2,3,0,1] row_mask:0xf bank_mask:0xf bound_ctrl:1
	ds_read_b128 v[22:25], v94 offset:26944
	ds_write_b32 v97, v74 offset:2312
	v_mov_b32_dpp v74, v74 row_mirror row_mask:0xf bank_mask:0xc
	v_pk_fma_f32 v[2:3], v[38:39], v[74:75], v[76:77] op_sel_hi:[1,0,1]
	v_pk_fma_f32 v[4:5], v[40:41], v[74:75], v[92:93] op_sel_hi:[1,0,1]
	s_waitcnt lgkmcnt(6)
	v_pk_mul_f32 v[70:71], v[2:3], v[46:47] op_sel_hi:[0,1]
	v_pk_mul_f32 v[72:73], v[2:3], v[48:49] op_sel:[1,0]
	v_pk_fma_f32 v[70:71], v[4:5], v[50:51], v[70:71] op_sel_hi:[0,1,1]
	v_pk_fma_f32 v[72:73], v[4:5], v[52:53], v[72:73] op_sel:[1,0,0]
	v_pk_add_f32 v[70:71], v[70:71], v[72:73]
	v_pk_mul_f32 v[76:77], v[62:63], v[66:67] op_sel_hi:[1,0]
	v_pk_mul_f32 v[92:93], v[64:65], v[66:67] op_sel_hi:[1,0]
	v_add_f32_dpp v74, v71, v70 row_mirror row_mask:0xf bank_mask:0xf bound_ctrl:1
	v_pk_fma_f32 v[76:77], v[2:3], v[54:55], v[76:77]
	v_pk_fma_f32 v[92:93], v[4:5], v[56:57], v[92:93]
	v_add_f32_dpp v74, v74, v74 row_half_mirror row_mask:0xf bank_mask:0xf bound_ctrl:1
	ds_read_b128 v[26:29], v94 offset:28160
	ds_read_b128 v[30:33], v94 offset:28176
	v_add_f32_dpp v74, v74, v74 quad_perm:[1,0,3,2] row_mask:0xf bank_mask:0xf bound_ctrl:1
	ds_read_b128 v[34:37], v94 offset:28192
	ds_read_b128 v[38:41], v94 offset:28208
	v_add_f32_dpp v74, v74, v74 quad_perm:[2,3,0,1] row_mask:0xf bank_mask:0xf bound_ctrl:1
	ds_read_b128 v[42:45], v94 offset:28224
	ds_write_b32 v97, v74 offset:2560
	ds_read2_b32 v[68:69], v96 offset0:96 offset1:112
	v_mov_b32_dpp v74, v74 row_mirror row_mask:0xf bank_mask:0xc
	v_pk_fma_f32 v[2:3], v[58:59], v[74:75], v[76:77] op_sel_hi:[1,0,1]
	v_pk_fma_f32 v[4:5], v[60:61], v[74:75], v[92:93] op_sel_hi:[1,0,1]
	s_waitcnt lgkmcnt(8)
	v_pk_mul_f32 v[70:71], v[2:3], v[6:7] op_sel_hi:[0,1]
	v_pk_mul_f32 v[72:73], v[2:3], v[8:9] op_sel:[1,0]
	v_pk_fma_f32 v[70:71], v[4:5], v[10:11], v[70:71] op_sel_hi:[0,1,1]
	v_pk_fma_f32 v[72:73], v[4:5], v[12:13], v[72:73] op_sel:[1,0,0]
	v_pk_add_f32 v[70:71], v[70:71], v[72:73]
	v_pk_mul_f32 v[76:77], v[22:23], v[66:67] op_sel:[0,1]
	v_pk_mul_f32 v[92:93], v[24:25], v[66:67] op_sel:[0,1]
	v_add_f32_dpp v74, v71, v70 row_mirror row_mask:0xf bank_mask:0xf bound_ctrl:1
	v_pk_fma_f32 v[76:77], v[2:3], v[14:15], v[76:77]
	v_pk_fma_f32 v[92:93], v[4:5], v[16:17], v[92:93]
	v_add_f32_dpp v74, v74, v74 row_half_mirror row_mask:0xf bank_mask:0xf bound_ctrl:1
	ds_read_b128 v[46:49], v94 offset:29440
	ds_read_b128 v[50:53], v94 offset:29456
	v_add_f32_dpp v74, v74, v74 quad_perm:[1,0,3,2] row_mask:0xf bank_mask:0xf bound_ctrl:1
	ds_read_b128 v[54:57], v94 offset:29472
	ds_read_b128 v[58:61], v94 offset:29488
	v_add_f32_dpp v74, v74, v74 quad_perm:[2,3,0,1] row_mask:0xf bank_mask:0xf bound_ctrl:1
	ds_read_b128 v[62:65], v94 offset:29504
	ds_write_b32 v97, v74 offset:2568
	v_mov_b32_dpp v74, v74 row_mirror row_mask:0xf bank_mask:0xc
	v_pk_fma_f32 v[2:3], v[18:19], v[74:75], v[76:77] op_sel_hi:[1,0,1]
	v_pk_fma_f32 v[4:5], v[20:21], v[74:75], v[92:93] op_sel_hi:[1,0,1]
	s_waitcnt lgkmcnt(6)
	v_pk_mul_f32 v[70:71], v[2:3], v[26:27] op_sel_hi:[0,1]
	v_pk_mul_f32 v[72:73], v[2:3], v[28:29] op_sel:[1,0]
	v_pk_fma_f32 v[70:71], v[4:5], v[30:31], v[70:71] op_sel_hi:[0,1,1]
	v_pk_fma_f32 v[72:73], v[4:5], v[32:33], v[72:73] op_sel:[1,0,0]
	v_pk_add_f32 v[70:71], v[70:71], v[72:73]
	v_pk_mul_f32 v[76:77], v[42:43], v[68:69] op_sel_hi:[1,0]
	v_pk_mul_f32 v[92:93], v[44:45], v[68:69] op_sel_hi:[1,0]
	v_add_f32_dpp v74, v71, v70 row_mirror row_mask:0xf bank_mask:0xf bound_ctrl:1
	v_pk_fma_f32 v[76:77], v[2:3], v[34:35], v[76:77]
	v_pk_fma_f32 v[92:93], v[4:5], v[36:37], v[92:93]
	v_add_f32_dpp v74, v74, v74 row_half_mirror row_mask:0xf bank_mask:0xf bound_ctrl:1
	ds_read_b128 v[6:9], v94 offset:30720
	ds_read_b128 v[10:13], v94 offset:30736
	v_add_f32_dpp v74, v74, v74 quad_perm:[1,0,3,2] row_mask:0xf bank_mask:0xf bound_ctrl:1
	ds_read_b128 v[14:17], v94 offset:30752
	ds_read_b128 v[18:21], v94 offset:30768
	v_add_f32_dpp v74, v74, v74 quad_perm:[2,3,0,1] row_mask:0xf bank_mask:0xf bound_ctrl:1
	ds_read_b128 v[22:25], v94 offset:30784
	ds_write_b32 v97, v74 offset:2816
	ds_read2_b32 v[66:67], v96 offset0:128 offset1:144
	v_mov_b32_dpp v74, v74 row_mirror row_mask:0xf bank_mask:0xc
	v_pk_fma_f32 v[2:3], v[38:39], v[74:75], v[76:77] op_sel_hi:[1,0,1]
	v_pk_fma_f32 v[4:5], v[40:41], v[74:75], v[92:93] op_sel_hi:[1,0,1]
	s_waitcnt lgkmcnt(8)
	v_pk_mul_f32 v[70:71], v[2:3], v[46:47] op_sel_hi:[0,1]
	v_pk_mul_f32 v[72:73], v[2:3], v[48:49] op_sel:[1,0]
	v_pk_fma_f32 v[70:71], v[4:5], v[50:51], v[70:71] op_sel_hi:[0,1,1]
	v_pk_fma_f32 v[72:73], v[4:5], v[52:53], v[72:73] op_sel:[1,0,0]
	v_pk_add_f32 v[70:71], v[70:71], v[72:73]
	v_pk_mul_f32 v[76:77], v[62:63], v[68:69] op_sel:[0,1]
	v_pk_mul_f32 v[92:93], v[64:65], v[68:69] op_sel:[0,1]
	v_add_f32_dpp v74, v71, v70 row_mirror row_mask:0xf bank_mask:0xf bound_ctrl:1
	v_pk_fma_f32 v[76:77], v[2:3], v[54:55], v[76:77]
	v_pk_fma_f32 v[92:93], v[4:5], v[56:57], v[92:93]
	v_add_f32_dpp v74, v74, v74 row_half_mirror row_mask:0xf bank_mask:0xf bound_ctrl:1
	ds_read_b128 v[26:29], v94 offset:32000
	ds_read_b128 v[30:33], v94 offset:32016
	v_add_f32_dpp v74, v74, v74 quad_perm:[1,0,3,2] row_mask:0xf bank_mask:0xf bound_ctrl:1
	ds_read_b128 v[34:37], v94 offset:32032
	ds_read_b128 v[38:41], v94 offset:32048
	v_add_f32_dpp v74, v74, v74 quad_perm:[2,3,0,1] row_mask:0xf bank_mask:0xf bound_ctrl:1
	ds_read_b128 v[42:45], v94 offset:32064
	ds_write_b32 v97, v74 offset:2824
	v_mov_b32_dpp v74, v74 row_mirror row_mask:0xf bank_mask:0xc
	v_pk_fma_f32 v[2:3], v[58:59], v[74:75], v[76:77] op_sel_hi:[1,0,1]
	v_pk_fma_f32 v[4:5], v[60:61], v[74:75], v[92:93] op_sel_hi:[1,0,1]
	s_waitcnt lgkmcnt(6)
	v_pk_mul_f32 v[70:71], v[2:3], v[6:7] op_sel_hi:[0,1]
	v_pk_mul_f32 v[72:73], v[2:3], v[8:9] op_sel:[1,0]
	v_pk_fma_f32 v[70:71], v[4:5], v[10:11], v[70:71] op_sel_hi:[0,1,1]
	v_pk_fma_f32 v[72:73], v[4:5], v[12:13], v[72:73] op_sel:[1,0,0]
	v_pk_add_f32 v[70:71], v[70:71], v[72:73]
	v_pk_mul_f32 v[76:77], v[22:23], v[66:67] op_sel_hi:[1,0]
	v_pk_mul_f32 v[92:93], v[24:25], v[66:67] op_sel_hi:[1,0]
	v_add_f32_dpp v74, v71, v70 row_mirror row_mask:0xf bank_mask:0xf bound_ctrl:1
	v_pk_fma_f32 v[76:77], v[2:3], v[14:15], v[76:77]
	v_pk_fma_f32 v[92:93], v[4:5], v[16:17], v[92:93]
	v_add_f32_dpp v74, v74, v74 row_half_mirror row_mask:0xf bank_mask:0xf bound_ctrl:1
	ds_read_b128 v[46:49], v94 offset:33280
	ds_read_b128 v[50:53], v94 offset:33296
	v_add_f32_dpp v74, v74, v74 quad_perm:[1,0,3,2] row_mask:0xf bank_mask:0xf bound_ctrl:1
	ds_read_b128 v[54:57], v94 offset:33312
	ds_read_b128 v[58:61], v94 offset:33328
	v_add_f32_dpp v74, v74, v74 quad_perm:[2,3,0,1] row_mask:0xf bank_mask:0xf bound_ctrl:1
	ds_read_b128 v[62:65], v94 offset:33344
	ds_write_b32 v97, v74 offset:3072
	ds_read2_b32 v[68:69], v96 offset0:160 offset1:176
	v_mov_b32_dpp v74, v74 row_mirror row_mask:0xf bank_mask:0xc
	v_pk_fma_f32 v[2:3], v[18:19], v[74:75], v[76:77] op_sel_hi:[1,0,1]
	v_pk_fma_f32 v[4:5], v[20:21], v[74:75], v[92:93] op_sel_hi:[1,0,1]
	s_waitcnt lgkmcnt(8)
	v_pk_mul_f32 v[70:71], v[2:3], v[26:27] op_sel_hi:[0,1]
	v_pk_mul_f32 v[72:73], v[2:3], v[28:29] op_sel:[1,0]
	v_pk_fma_f32 v[70:71], v[4:5], v[30:31], v[70:71] op_sel_hi:[0,1,1]
	v_pk_fma_f32 v[72:73], v[4:5], v[32:33], v[72:73] op_sel:[1,0,0]
	v_pk_add_f32 v[70:71], v[70:71], v[72:73]
	v_pk_mul_f32 v[76:77], v[42:43], v[66:67] op_sel:[0,1]
	v_pk_mul_f32 v[92:93], v[44:45], v[66:67] op_sel:[0,1]
	v_add_f32_dpp v74, v71, v70 row_mirror row_mask:0xf bank_mask:0xf bound_ctrl:1
	v_pk_fma_f32 v[76:77], v[2:3], v[34:35], v[76:77]
	v_pk_fma_f32 v[92:93], v[4:5], v[36:37], v[92:93]
	v_add_f32_dpp v74, v74, v74 row_half_mirror row_mask:0xf bank_mask:0xf bound_ctrl:1
	ds_read_b128 v[6:9], v94 offset:34560
	ds_read_b128 v[10:13], v94 offset:34576
	v_add_f32_dpp v74, v74, v74 quad_perm:[1,0,3,2] row_mask:0xf bank_mask:0xf bound_ctrl:1
	ds_read_b128 v[14:17], v94 offset:34592
	ds_read_b128 v[18:21], v94 offset:34608
	v_add_f32_dpp v74, v74, v74 quad_perm:[2,3,0,1] row_mask:0xf bank_mask:0xf bound_ctrl:1
	ds_read_b128 v[22:25], v94 offset:34624
	ds_write_b32 v97, v74 offset:3080
	v_mov_b32_dpp v74, v74 row_mirror row_mask:0xf bank_mask:0xc
	v_pk_fma_f32 v[2:3], v[38:39], v[74:75], v[76:77] op_sel_hi:[1,0,1]
	v_pk_fma_f32 v[4:5], v[40:41], v[74:75], v[92:93] op_sel_hi:[1,0,1]
	s_waitcnt lgkmcnt(6)
	v_pk_mul_f32 v[70:71], v[2:3], v[46:47] op_sel_hi:[0,1]
	v_pk_mul_f32 v[72:73], v[2:3], v[48:49] op_sel:[1,0]
	v_pk_fma_f32 v[70:71], v[4:5], v[50:51], v[70:71] op_sel_hi:[0,1,1]
	v_pk_fma_f32 v[72:73], v[4:5], v[52:53], v[72:73] op_sel:[1,0,0]
	v_pk_add_f32 v[70:71], v[70:71], v[72:73]
	v_pk_mul_f32 v[76:77], v[62:63], v[68:69] op_sel_hi:[1,0]
	v_pk_mul_f32 v[92:93], v[64:65], v[68:69] op_sel_hi:[1,0]
	v_add_f32_dpp v74, v71, v70 row_mirror row_mask:0xf bank_mask:0xf bound_ctrl:1
	v_pk_fma_f32 v[76:77], v[2:3], v[54:55], v[76:77]
	v_pk_fma_f32 v[92:93], v[4:5], v[56:57], v[92:93]
	v_add_f32_dpp v74, v74, v74 row_half_mirror row_mask:0xf bank_mask:0xf bound_ctrl:1
	ds_read_b128 v[26:29], v94 offset:35840
	ds_read_b128 v[30:33], v94 offset:35856
	v_add_f32_dpp v74, v74, v74 quad_perm:[1,0,3,2] row_mask:0xf bank_mask:0xf bound_ctrl:1
	ds_read_b128 v[34:37], v94 offset:35872
	ds_read_b128 v[38:41], v94 offset:35888
	v_add_f32_dpp v74, v74, v74 quad_perm:[2,3,0,1] row_mask:0xf bank_mask:0xf bound_ctrl:1
	ds_read_b128 v[42:45], v94 offset:35904
	ds_write_b32 v97, v74 offset:3328
	ds_read2_b32 v[66:67], v96 offset0:192 offset1:208
	v_mov_b32_dpp v74, v74 row_mirror row_mask:0xf bank_mask:0xc
	v_pk_fma_f32 v[2:3], v[58:59], v[74:75], v[76:77] op_sel_hi:[1,0,1]
	v_pk_fma_f32 v[4:5], v[60:61], v[74:75], v[92:93] op_sel_hi:[1,0,1]
	s_waitcnt lgkmcnt(8)
	v_pk_mul_f32 v[70:71], v[2:3], v[6:7] op_sel_hi:[0,1]
	v_pk_mul_f32 v[72:73], v[2:3], v[8:9] op_sel:[1,0]
	v_pk_fma_f32 v[70:71], v[4:5], v[10:11], v[70:71] op_sel_hi:[0,1,1]
	v_pk_fma_f32 v[72:73], v[4:5], v[12:13], v[72:73] op_sel:[1,0,0]
	v_pk_add_f32 v[70:71], v[70:71], v[72:73]
	v_pk_mul_f32 v[76:77], v[22:23], v[68:69] op_sel:[0,1]
	v_pk_mul_f32 v[92:93], v[24:25], v[68:69] op_sel:[0,1]
	v_add_f32_dpp v74, v71, v70 row_mirror row_mask:0xf bank_mask:0xf bound_ctrl:1
	v_pk_fma_f32 v[76:77], v[2:3], v[14:15], v[76:77]
	v_pk_fma_f32 v[92:93], v[4:5], v[16:17], v[92:93]
	v_add_f32_dpp v74, v74, v74 row_half_mirror row_mask:0xf bank_mask:0xf bound_ctrl:1
	ds_read_b128 v[46:49], v94 offset:37120
	ds_read_b128 v[50:53], v94 offset:37136
	v_add_f32_dpp v74, v74, v74 quad_perm:[1,0,3,2] row_mask:0xf bank_mask:0xf bound_ctrl:1
	ds_read_b128 v[54:57], v94 offset:37152
	ds_read_b128 v[58:61], v94 offset:37168
	v_add_f32_dpp v74, v74, v74 quad_perm:[2,3,0,1] row_mask:0xf bank_mask:0xf bound_ctrl:1
	ds_read_b128 v[62:65], v94 offset:37184
	ds_write_b32 v97, v74 offset:3336
	v_mov_b32_dpp v74, v74 row_mirror row_mask:0xf bank_mask:0xc
	v_pk_fma_f32 v[2:3], v[18:19], v[74:75], v[76:77] op_sel_hi:[1,0,1]
	v_pk_fma_f32 v[4:5], v[20:21], v[74:75], v[92:93] op_sel_hi:[1,0,1]
	s_waitcnt lgkmcnt(6)
	v_pk_mul_f32 v[70:71], v[2:3], v[26:27] op_sel_hi:[0,1]
	v_pk_mul_f32 v[72:73], v[2:3], v[28:29] op_sel:[1,0]
	v_pk_fma_f32 v[70:71], v[4:5], v[30:31], v[70:71] op_sel_hi:[0,1,1]
	v_pk_fma_f32 v[72:73], v[4:5], v[32:33], v[72:73] op_sel:[1,0,0]
	v_pk_add_f32 v[70:71], v[70:71], v[72:73]
	v_pk_mul_f32 v[76:77], v[42:43], v[66:67] op_sel_hi:[1,0]
	v_pk_mul_f32 v[92:93], v[44:45], v[66:67] op_sel_hi:[1,0]
	v_add_f32_dpp v74, v71, v70 row_mirror row_mask:0xf bank_mask:0xf bound_ctrl:1
	v_pk_fma_f32 v[76:77], v[2:3], v[34:35], v[76:77]
	v_pk_fma_f32 v[92:93], v[4:5], v[36:37], v[92:93]
	v_add_f32_dpp v74, v74, v74 row_half_mirror row_mask:0xf bank_mask:0xf bound_ctrl:1
	ds_read_b128 v[6:9], v94 offset:38400
	ds_read_b128 v[10:13], v94 offset:38416
	v_add_f32_dpp v74, v74, v74 quad_perm:[1,0,3,2] row_mask:0xf bank_mask:0xf bound_ctrl:1
	ds_read_b128 v[14:17], v94 offset:38432
	ds_read_b128 v[18:21], v94 offset:38448
	v_add_f32_dpp v74, v74, v74 quad_perm:[2,3,0,1] row_mask:0xf bank_mask:0xf bound_ctrl:1
	ds_read_b128 v[22:25], v94 offset:38464
	ds_write_b32 v97, v74 offset:3584
	ds_read2_b32 v[68:69], v96 offset0:224 offset1:240
	v_mov_b32_dpp v74, v74 row_mirror row_mask:0xf bank_mask:0xc
	v_pk_fma_f32 v[2:3], v[38:39], v[74:75], v[76:77] op_sel_hi:[1,0,1]
	v_pk_fma_f32 v[4:5], v[40:41], v[74:75], v[92:93] op_sel_hi:[1,0,1]
	s_waitcnt lgkmcnt(8)
	v_pk_mul_f32 v[70:71], v[2:3], v[46:47] op_sel_hi:[0,1]
	v_pk_mul_f32 v[72:73], v[2:3], v[48:49] op_sel:[1,0]
	v_pk_fma_f32 v[70:71], v[4:5], v[50:51], v[70:71] op_sel_hi:[0,1,1]
	v_pk_fma_f32 v[72:73], v[4:5], v[52:53], v[72:73] op_sel:[1,0,0]
	v_pk_add_f32 v[70:71], v[70:71], v[72:73]
	v_pk_mul_f32 v[76:77], v[62:63], v[66:67] op_sel:[0,1]
	v_pk_mul_f32 v[92:93], v[64:65], v[66:67] op_sel:[0,1]
	v_add_f32_dpp v74, v71, v70 row_mirror row_mask:0xf bank_mask:0xf bound_ctrl:1
	v_pk_fma_f32 v[76:77], v[2:3], v[54:55], v[76:77]
	v_pk_fma_f32 v[92:93], v[4:5], v[56:57], v[92:93]
	v_add_f32_dpp v74, v74, v74 row_half_mirror row_mask:0xf bank_mask:0xf bound_ctrl:1
	ds_read_b128 v[26:29], v94 offset:39680
	ds_read_b128 v[30:33], v94 offset:39696
	v_add_f32_dpp v74, v74, v74 quad_perm:[1,0,3,2] row_mask:0xf bank_mask:0xf bound_ctrl:1
	ds_read_b128 v[34:37], v94 offset:39712
	ds_read_b128 v[38:41], v94 offset:39728
	v_add_f32_dpp v74, v74, v74 quad_perm:[2,3,0,1] row_mask:0xf bank_mask:0xf bound_ctrl:1
	ds_read_b128 v[42:45], v94 offset:39744
	ds_write_b32 v97, v74 offset:3592
	v_mov_b32_dpp v74, v74 row_mirror row_mask:0xf bank_mask:0xc
	v_pk_fma_f32 v[2:3], v[58:59], v[74:75], v[76:77] op_sel_hi:[1,0,1]
	v_pk_fma_f32 v[4:5], v[60:61], v[74:75], v[92:93] op_sel_hi:[1,0,1]
	s_waitcnt lgkmcnt(6)
	v_pk_mul_f32 v[70:71], v[2:3], v[6:7] op_sel_hi:[0,1]
	v_pk_mul_f32 v[72:73], v[2:3], v[8:9] op_sel:[1,0]
	v_pk_fma_f32 v[70:71], v[4:5], v[10:11], v[70:71] op_sel_hi:[0,1,1]
	v_pk_fma_f32 v[72:73], v[4:5], v[12:13], v[72:73] op_sel:[1,0,0]
	v_pk_add_f32 v[70:71], v[70:71], v[72:73]
	v_pk_mul_f32 v[76:77], v[22:23], v[68:69] op_sel_hi:[1,0]
	v_pk_mul_f32 v[92:93], v[24:25], v[68:69] op_sel_hi:[1,0]
	v_add_f32_dpp v74, v71, v70 row_mirror row_mask:0xf bank_mask:0xf bound_ctrl:1
	v_pk_fma_f32 v[76:77], v[2:3], v[14:15], v[76:77]
	v_pk_fma_f32 v[92:93], v[4:5], v[16:17], v[92:93]
	v_add_f32_dpp v74, v74, v74 row_half_mirror row_mask:0xf bank_mask:0xf bound_ctrl:1
	s_nop 1
	v_add_f32_dpp v74, v74, v74 quad_perm:[1,0,3,2] row_mask:0xf bank_mask:0xf bound_ctrl:1
	s_nop 1
	v_add_f32_dpp v74, v74, v74 quad_perm:[2,3,0,1] row_mask:0xf bank_mask:0xf bound_ctrl:1
	s_nop 0
	ds_write_b32 v97, v74 offset:3840
	v_mov_b32_dpp v74, v74 row_mirror row_mask:0xf bank_mask:0xc
	v_pk_fma_f32 v[2:3], v[18:19], v[74:75], v[76:77] op_sel_hi:[1,0,1]
	v_pk_fma_f32 v[4:5], v[20:21], v[74:75], v[92:93] op_sel_hi:[1,0,1]
	s_waitcnt lgkmcnt(2)
	v_pk_mul_f32 v[70:71], v[2:3], v[26:27] op_sel_hi:[0,1]
	v_pk_mul_f32 v[72:73], v[2:3], v[28:29] op_sel:[1,0]
	v_pk_fma_f32 v[70:71], v[4:5], v[30:31], v[70:71] op_sel_hi:[0,1,1]
	v_pk_fma_f32 v[72:73], v[4:5], v[32:33], v[72:73] op_sel:[1,0,0]
	v_pk_add_f32 v[70:71], v[70:71], v[72:73]
	v_pk_mul_f32 v[76:77], v[42:43], v[68:69] op_sel:[0,1]
	v_pk_mul_f32 v[92:93], v[44:45], v[68:69] op_sel:[0,1]
	v_add_f32_dpp v74, v71, v70 row_mirror row_mask:0xf bank_mask:0xf bound_ctrl:1
	v_pk_fma_f32 v[76:77], v[2:3], v[34:35], v[76:77]
	v_pk_fma_f32 v[92:93], v[4:5], v[36:37], v[92:93]
	v_add_f32_dpp v74, v74, v74 row_half_mirror row_mask:0xf bank_mask:0xf bound_ctrl:1
	s_nop 1
	v_add_f32_dpp v74, v74, v74 quad_perm:[1,0,3,2] row_mask:0xf bank_mask:0xf bound_ctrl:1
	s_nop 1
	v_add_f32_dpp v74, v74, v74 quad_perm:[2,3,0,1] row_mask:0xf bank_mask:0xf bound_ctrl:1
	s_nop 0
	ds_write_b32 v97, v74 offset:3848
	v_mov_b32_dpp v74, v74 row_mirror row_mask:0xf bank_mask:0xc
	v_pk_fma_f32 v[2:3], v[38:39], v[74:75], v[76:77] op_sel_hi:[1,0,1]
	v_pk_fma_f32 v[4:5], v[40:41], v[74:75], v[92:93] op_sel_hi:[1,0,1]
	s_add_i32 s33, s33, 1
	s_cmpk_lg_i32 s33, 0x80
	s_waitcnt lgkmcnt(0)
	s_barrier
	s_cbranch_scc1 .Lscan_chunk

.LBB0_914:
	v_lshlrev_b32_e32 v112, 16, v59
	v_and_b32_e32 v118, 0xffff0000, v59
	v_lshlrev_b32_e32 v59, 16, v54
	v_lshlrev_b32_e32 v120, 16, v60
	v_and_b32_e32 v122, 0xffff0000, v60
	v_and_b32_e32 v60, 0xffff0000, v54
	v_lshlrev_b32_e32 v127, 16, v50
	v_lshlrev_b32_e32 v126, 16, v46
	v_and_b32_e32 v131, 0xffff0000, v50
	v_and_b32_e32 v130, 0xffff0000, v46
	v_lshlrev_b32_e32 v46, 16, v48
	v_and_b32_e32 v50, 0xffff0000, v48
	v_mul_f32_e32 v48, 0x3fb8aa3b, v59
	v_lshlrev_b32_e32 v124, 16, v61
	v_and_b32_e32 v134, 0xffff0000, v61
	v_lshlrev_b32_e32 v61, 16, v55
	v_exp_f32_e32 v54, v48
	v_mul_f32_e32 v48, 0x3fb8aa3b, v60
	v_and_b32_e32 v109, 0xffff0000, v55
	v_exp_f32_e32 v55, v48
	v_mul_f32_e32 v48, 0x3fb8aa3b, v61
	v_lshlrev_b32_e32 v113, 16, v56
	v_and_b32_e32 v115, 0xffff0000, v56
	v_exp_f32_e32 v56, v48
	v_mul_f32_e32 v48, 0x3fb8aa3b, v109
	v_lshlrev_b32_e32 v116, 16, v57
	v_and_b32_e32 v121, 0xffff0000, v57
	v_exp_f32_e32 v57, v48
	v_mul_f32_e32 v48, 0x3fb8aa3b, v113
	v_and_b32_e32 v128, 0xffff0000, v47
	v_lshlrev_b32_e32 v133, 16, v51
	v_lshlrev_b32_e32 v132, 16, v47
	v_and_b32_e32 v129, 0xffff0000, v51
	v_exp_f32_e32 v114, v48
	v_mul_f32_e32 v48, 0x3fb8aa3b, v115
	v_lshlrev_b32_e32 v47, 16, v52
	v_and_b32_e32 v51, 0xffff0000, v52
	v_lshlrev_b32_e32 v136, 16, v49
	v_and_b32_e32 v52, 0xffff0000, v49
	v_add_f32_e32 v49, -1.0, v126
	v_add_f32_e32 v141, -1.0, v132
	v_add_f32_e32 v143, -1.0, v128
	v_exp_f32_e32 v115, v48
	v_mov_b32_e32 v142, v129
	v_mov_b32_e32 v140, v133
	v_mov_b32_e32 v48, v127
	v_add_f32_e32 v139, -1.0, v130
	v_pk_mul_f32 v[162:163], v[68:69], v[142:143]
	v_pk_mul_f32 v[164:165], v[20:21], v[140:141]
	v_mov_b32_e32 v138, v131
	v_pk_mul_f32 v[170:171], v[18:19], v[48:49]
	v_add_f32_e32 v145, -1.0, v46
	v_add_f32_e32 v147, -1.0, v50
	v_mov_b32_e32 v146, v51
	v_mov_b32_e32 v144, v47
	v_mov_b32_e32 v166, v162
	v_mov_b32_e32 v167, v164
	v_pk_mul_f32 v[168:169], v[70:71], v[138:139]
	v_mul_f32_e32 v109, v170, v170
	v_lshlrev_b32_e32 v137, 16, v53
	v_and_b32_e32 v53, 0xffff0000, v53
	v_pk_mul_f32 v[156:157], v[66:67], v[146:147]
	v_pk_mul_f32 v[158:159], v[22:23], v[144:145]
	v_pk_mul_f32 v[166:167], v[166:167], v[166:167]
	v_fmac_f32_e32 v109, v168, v168
	v_add_f32_e32 v149, -1.0, v136
	v_add_f32_e32 v151, -1.0, v52
	v_mov_b32_e32 v150, v53
	v_mov_b32_e32 v148, v137
	v_mov_b32_e32 v160, v156
	v_mov_b32_e32 v161, v158
	v_add_f32_e32 v109, v167, v109
	v_pk_mul_f32 v[152:153], v[64:65], v[150:151]
	v_pk_mul_f32 v[154:155], v[24:25], v[148:149]
	v_pk_mul_f32 v[160:161], v[160:161], v[160:161]
	v_add_f32_e32 v109, v166, v109
	v_mul_f32_e32 v60, 0x3fb8aa3b, v116
	v_mov_b32_e32 v116, v152
	v_mov_b32_e32 v117, v154
	v_add_f32_e32 v109, v161, v109
	v_pk_mul_f32 v[116:117], v[116:117], v[116:117]
	v_add_f32_e32 v109, v160, v109
	v_add_f32_e32 v109, v117, v109
	v_add_f32_e32 v109, v116, v109
	v_exp_f32_e32 v116, v60
	v_mul_f32_e32 v60, 0x3fb8aa3b, v121
	v_add_f32_dpp v109, v109, v109 row_half_mirror row_mask:0xf bank_mask:0xf bound_ctrl:1
	v_exp_f32_e32 v117, v60
	v_pk_fma_f32 v[48:49], v[18:19], v[48:49], s[16:17]
	v_add_f32_dpp v109, v109, v109 quad_perm:[1,0,3,2] row_mask:0xf bank_mask:0xf bound_ctrl:1
	v_lshlrev_b32_e32 v110, 16, v58
	v_and_b32_e32 v58, 0xffff0000, v58
	v_add_f32_dpp v109, v109, v109 quad_perm:[2,3,0,1] row_mask:0xf bank_mask:0xf bound_ctrl:1
	v_sqrt_f32_e32 v109, v109
	v_mul_f32_e32 v59, v54, v110
	v_mul_f32_e32 v113, v57, v118
	v_mul_f32_e32 v111, v56, v112
	v_max_f32_e32 v60, 0x2b8cbccc, v109
	v_rcp_f32_e32 v178, v60
	v_mul_f32_e32 v119, v114, v120
	v_mul_f32_e32 v121, v115, v122
	v_mul_f32_e32 v123, v116, v124
	v_pk_mul_f32 v[160:161], v[170:171], v[178:179]
	v_pk_mul_f32 v[168:169], v[168:169], v[178:179]
	v_mov_b32_e32 v161, v49
	v_pk_mul_f32 v[166:167], v[160:161], v[126:127]
	v_pk_fma_f32 v[126:127], v[70:71], v[138:139], s[16:17]
	v_mul_f32_e32 v48, v167, v110
	v_mov_b32_e32 v169, v127
	v_pk_mul_f32 v[126:127], v[168:169], v[130:131]
	v_fma_f32 v109, v26, v48, 0
	v_pk_mul_f32 v[130:131], v[126:127], v[58:59] op_sel_hi:[1,0]
	v_pk_mul_f32 v[138:139], v[164:165], v[178:179]
	v_fmac_f32_e32 v109, v27, v131
	v_pk_fma_f32 v[130:131], v[20:21], v[140:141], s[16:17]
	v_pk_fma_f32 v[48:49], v[166:167], v[110:111], 0 op_sel_hi:[1,0,0]
	v_mov_b32_e32 v139, v131
	v_pk_mul_f32 v[140:141], v[138:139], v[132:133]
	v_pk_fma_f32 v[132:133], v[68:69], v[142:143], s[16:17]
	v_pk_mul_f32 v[130:131], v[140:141], v[112:113] op_sel_hi:[1,0]
	v_pk_fma_f32 v[48:49], v[126:127], v[58:59], v[48:49] op_sel_hi:[1,0,1]
	v_fmac_f32_e32 v109, v28, v131
	v_pk_mul_f32 v[130:131], v[162:163], v[178:179]
	v_pk_fma_f32 v[48:49], v[140:141], v[112:113], v[48:49] op_sel_hi:[1,0,1]
	v_mov_b32_e32 v131, v133
	v_pk_mul_f32 v[128:129], v[130:131], v[128:129]
	v_xor_b32_e32 v112, 0x80000000, v130
	v_pk_mul_f32 v[130:131], v[128:129], v[118:119] op_sel_hi:[1,0]
	v_pk_mul_f32 v[142:143], v[158:159], v[178:179]
	v_fmac_f32_e32 v109, v29, v131
	v_pk_fma_f32 v[130:131], v[22:23], v[144:145], s[16:17]
	v_pk_fma_f32 v[48:49], v[128:129], v[118:119], v[48:49] op_sel_hi:[1,0,1]
	v_mov_b32_e32 v143, v131
	v_pk_mul_f32 v[144:145], v[142:143], v[46:47]
	v_pk_fma_f32 v[130:131], v[66:67], v[146:147], s[16:17]
	v_pk_mul_f32 v[46:47], v[144:145], v[120:121] op_sel_hi:[1,0]
	v_pk_fma_f32 v[48:49], v[144:145], v[120:121], v[48:49] op_sel_hi:[1,0,1]
	v_fmac_f32_e32 v109, v30, v47
	v_pk_mul_f32 v[46:47], v[156:157], v[178:179]
	v_pk_mul_f32 v[146:147], v[154:155], v[178:179]
	v_mov_b32_e32 v47, v131
	v_pk_mul_f32 v[130:131], v[46:47], v[50:51]
	v_xor_b32_e32 v120, 0x80000000, v46
	v_pk_mul_f32 v[46:47], v[130:131], v[122:123] op_sel_hi:[1,0]
	v_mul_f32_e32 v125, v117, v134
	v_fmac_f32_e32 v109, v31, v47
	v_pk_fma_f32 v[46:47], v[24:25], v[148:149], s[16:17]
	v_pk_fma_f32 v[50:51], v[64:65], v[150:151], s[16:17]
	v_mov_b32_e32 v147, v47
	v_pk_mul_f32 v[136:137], v[146:147], v[136:137]
	v_pk_fma_f32 v[48:49], v[130:131], v[122:123], v[48:49] op_sel_hi:[1,0,1]
	v_pk_mul_f32 v[46:47], v[136:137], v[124:125] op_sel_hi:[1,0]
	v_pk_fma_f32 v[48:49], v[136:137], v[124:125], v[48:49] op_sel_hi:[1,0,1]
	v_fmac_f32_e32 v109, v32, v47
	v_pk_mul_f32 v[46:47], v[152:153], v[178:179]
	v_mul_f32_e32 v61, v55, v58
	v_mov_b32_e32 v47, v51
	v_pk_mul_f32 v[132:133], v[46:47], v[52:53]
	v_xor_b32_e32 v124, 0x80000000, v46
	v_pk_mul_f32 v[46:47], v[132:133], v[134:135] op_sel_hi:[1,0]
	v_pk_fma_f32 v[48:49], v[132:133], v[134:135], v[48:49] op_sel_hi:[1,0,1]
	v_lshl_add_u32 v52, s47, 5, v78
	v_fmac_f32_e32 v109, v33, v47
	v_mov_b32_dpp v46, v48 row_half_mirror row_mask:0xf bank_mask:0xf bound_ctrl:1
	v_mov_b32_dpp v47, v49 row_half_mirror row_mask:0xf bank_mask:0xf bound_ctrl:1
	v_lshl_or_b32 v53, v52, 4, v80
	v_pk_add_f32 v[46:47], v[48:49], v[46:47]
	v_mul_lo_u32 v53, v53, s42
	v_xor_b32_e32 v60, 0x80000000, v168
	v_mov_b32_dpp v48, v46 quad_perm:[1,0,3,2] row_mask:0xf bank_mask:0xf bound_ctrl:1
	v_mov_b32_dpp v49, v47 quad_perm:[1,0,3,2] row_mask:0xf bank_mask:0xf bound_ctrl:1
	v_add_f32_dpp v50, v109, v109 row_half_mirror row_mask:0xf bank_mask:0xf bound_ctrl:1
	v_add_u32_e32 v53, s14, v53
	v_xor_b32_e32 v58, 0x80000000, v160
	v_xor_b32_e32 v110, 0x80000000, v138
	v_pk_add_f32 v[46:47], v[46:47], v[48:49]
	v_add_f32_dpp v50, v50, v50 quad_perm:[1,0,3,2] row_mask:0xf bank_mask:0xf bound_ctrl:1
	v_and_b32_e32 v172, 4, v200
	v_cmp_ne_u32_e64 s[100:101], 0, v172
	s_nop 1
	v_cndmask_b32_e64 v172, v58, v59, s[100:101]
	v_cndmask_b32_e64 v173, v59, v58, s[100:101]
	v_cndmask_b32_e64 v174, v60, v61, s[100:101]
	v_cndmask_b32_e64 v175, v61, v60, s[100:101]
	ds_write_b128 v53, v[172:175]
	v_cndmask_b32_e64 v172, v110, v111, s[100:101]
	v_cndmask_b32_e64 v173, v111, v110, s[100:101]
	v_cndmask_b32_e64 v174, v112, v113, s[100:101]
	v_cndmask_b32_e64 v175, v113, v112, s[100:101]
	ds_write_b128 v53, v[172:175] offset:16
	ds_write_b128 v53, v[54:57] offset:32
	v_mov_b32_e32 v54, v166
	v_mov_b32_e32 v55, v126
	v_mov_b32_e32 v56, v140
	v_mov_b32_e32 v57, v128
	v_mov_b32_dpp v48, v46 quad_perm:[2,3,0,1] row_mask:0xf bank_mask:0xf bound_ctrl:1
	v_mov_b32_dpp v49, v47 quad_perm:[2,3,0,1] row_mask:0xf bank_mask:0xf bound_ctrl:1
	v_mov_b32_dpp v51, v50 quad_perm:[2,3,0,1] row_mask:0xf bank_mask:0xf bound_ctrl:1
	ds_write_b128 v53, v[54:57] offset:48
	v_mov_b32_e32 v126, v167
	v_mov_b32_e32 v128, v141
	v_xor_b32_e32 v118, 0x80000000, v142
	v_xor_b32_e32 v122, 0x80000000, v146
	v_mov_b32_e32 v54, v144
	v_mov_b32_e32 v55, v130
	v_mov_b32_e32 v56, v136
	v_mov_b32_e32 v57, v132
	v_mov_b32_e32 v130, v145
	v_mov_b32_e32 v132, v137
	ds_write_b128 v53, v[126:129] offset:64
	v_cndmask_b32_e64 v172, v118, v119, s[100:101]
	v_cndmask_b32_e64 v173, v119, v118, s[100:101]
	v_cndmask_b32_e64 v174, v120, v121, s[100:101]
	v_cndmask_b32_e64 v175, v121, v120, s[100:101]
	ds_write_b128 v53, v[172:175] offset:80
	v_cndmask_b32_e64 v172, v122, v123, s[100:101]
	v_cndmask_b32_e64 v173, v123, v122, s[100:101]
	v_cndmask_b32_e64 v174, v124, v125, s[100:101]
	v_cndmask_b32_e64 v175, v125, v124, s[100:101]
	ds_write_b128 v53, v[172:175] offset:96
	ds_write_b128 v53, v[114:117] offset:112
	ds_write_b128 v53, v[54:57] offset:128
	ds_write_b128 v53, v[130:133] offset:144
	s_and_saveexec_b64 s[78:79], s[10:11]
	s_cbranch_execz .LBB0_894
	v_lshl_add_u32 v52, v52, 3, s16
	v_pk_add_f32 v[46:47], v[46:47], v[48:49]
	s_andn2_b64 vcc, exec, s[72:73]
	ds_write2_b32 v52, v46, v47 offset1:1
	s_cbranch_vccnz .LBB0_894
	v_add_f32_e32 v46, v50, v51
	flat_store_dword v[92:93], v46
	s_branch .LBB0_894

	.amdhsa_kernel _Z8mega_fwd6Params
		.amdhsa_group_segment_fixed_size 0
		.amdhsa_private_segment_fixed_size 0
		.amdhsa_kernarg_size 496
		.amdhsa_user_sgpr_count 2
		.amdhsa_user_sgpr_dispatch_ptr 0
		.amdhsa_user_sgpr_queue_ptr 0
		.amdhsa_user_sgpr_kernarg_segment_ptr 1
		.amdhsa_user_sgpr_dispatch_id 0
		.amdhsa_user_sgpr_kernarg_preload_length 0
		.amdhsa_user_sgpr_kernarg_preload_offset 0
		.amdhsa_user_sgpr_private_segment_size 0
		.amdhsa_uses_dynamic_stack 0
		.amdhsa_enable_private_segment 0
		.amdhsa_system_sgpr_workgroup_id_x 1
		.amdhsa_system_sgpr_workgroup_id_y 0
		.amdhsa_system_sgpr_workgroup_id_z 0
		.amdhsa_system_sgpr_workgroup_info 0
		.amdhsa_system_vgpr_workitem_id 2
		.amdhsa_next_free_vgpr 253
		.amdhsa_next_free_sgpr 102
		.amdhsa_accum_offset 256
		.amdhsa_reserve_vcc 1
		.amdhsa_float_round_mode_32 0
		.amdhsa_float_round_mode_16_64 0
		.amdhsa_float_denorm_mode_32 3
		.amdhsa_float_denorm_mode_16_64 3
		.amdhsa_dx10_clamp 1
		.amdhsa_ieee_mode 1
		.amdhsa_fp16_overflow 0
		.amdhsa_tg_split 0
		.amdhsa_exception_fp_ieee_invalid_op 0
		.amdhsa_exception_fp_denorm_src 0
		.amdhsa_exception_fp_ieee_div_zero 0
		.amdhsa_exception_fp_ieee_overflow 0
		.amdhsa_exception_fp_ieee_underflow 0
		.amdhsa_exception_fp_ieee_inexact 0
		.amdhsa_exception_int_div_zero 0
	.end_amdhsa_kernel

amdhsa.kernels:
  - .agpr_count:     0
    .args:
      - .offset:         0
        .size:           240
        .value_kind:     by_value
      - .offset:         240
        .size:           4
        .value_kind:     hidden_block_count_x
      - .offset:         244
        .size:           4
        .value_kind:     hidden_block_count_y
      - .offset:         248
        .size:           4
        .value_kind:     hidden_block_count_z
      - .offset:         252
        .size:           2
        .value_kind:     hidden_group_size_x
      - .offset:         254
        .size:           2
        .value_kind:     hidden_group_size_y
      - .offset:         256
        .size:           2
        .value_kind:     hidden_group_size_z
      - .offset:         258
        .size:           2
        .value_kind:     hidden_remainder_x
      - .offset:         260
        .size:           2
        .value_kind:     hidden_remainder_y
      - .offset:         262
        .size:           2
        .value_kind:     hidden_remainder_z
      - .offset:         280
        .size:           8
        .value_kind:     hidden_global_offset_x
      - .offset:         288
        .size:           8
        .value_kind:     hidden_global_offset_y
      - .offset:         296
        .size:           8
        .value_kind:     hidden_global_offset_z
      - .offset:         304
        .size:           2
        .value_kind:     hidden_grid_dims
      - .offset:         328
        .size:           8
        .value_kind:     hidden_multigrid_sync_arg
      - .offset:         360
        .size:           4
        .value_kind:     hidden_dynamic_lds_size
    .group_segment_fixed_size: 0
    .kernarg_segment_align: 8
    .kernarg_segment_size: 496
    .language:       OpenCL C
    .language_version:
      - 2
      - 0
    .max_flat_workgroup_size: 512
    .name:           _Z8mega_fwd6Params
    .private_segment_fixed_size: 0
    .sgpr_count:     108
    .sgpr_spill_count: 37
    .symbol:         _Z8mega_fwd6Params.kd
    .uniform_work_group_size: 1
    .uses_dynamic_stack: false
    .vgpr_count:     253
    .vgpr_spill_count: 0
    .wavefront_size: 64
